# speedup vs baseline: 1.0104x; 1.0021x over previous
; __global__ void __launch_bounds__(NTHR, 2) hymba_fwd(Args args) {
;     ...
;     for (int ph = lo; ph < hi; ++ph) {
;         int l = ph / NPH; const int k = ph % NPH;
;         if (k == 3 || k == 11) continue;
;         asm volatile("" : "+s"(l));
;         int G = gridDim.x, bid = blockIdx.x; asm volatile("" : "+s"(G), "+s"(bid));
.LBB0_20:
	s_lshr_b32 s5, s54, 1
	s_mul_hi_i32 s0, s5, 0x92492493
	s_add_i32 s0, s0, s5
	s_lshr_b32 s1, s0, 31
	s_ashr_i32 s0, s0, 3
	s_add_i32 s4, s0, s1
	s_mul_i32 s0, s4, 14
	s_sub_i32 s5, s5, s0
	s_cmp_eq_u32 s5, 1
	s_cselect_b32 s0, 1, 0
	s_cmp_eq_u32 s5, 4
	s_cselect_b32 s1, 1, 0
	s_or_b32 s0, s0, s1
	s_cmp_eq_u32 s5, 12
	s_cselect_b32 s1, 1, 0
	s_cmp_eq_u32 s4, 0
	s_cselect_b32 s1, s1, 0
	s_or_b32 s0, s0, s1
	v_readlane_b32 s1, v253, 1
	s_cmp_eq_u32 s1, 0x100
	s_cselect_b32 s0, s0, 0
	s_bitcmp1_b32 s54, 0
	s_cbranch_scc1 .Lhdr_rep1
	s_cmp_eq_u32 s5, 0
	s_cselect_b32 s1, 1, 0
	s_cmp_eq_u32 s4, 1
	s_cselect_b32 s1, s1, 0
	v_readlane_b32 s12, v253, 1
	s_cmp_eq_u32 s12, 0x100
	s_cselect_b32 s1, s1, 0
	s_or_b32 s0, s0, s1
	v_writelane_b32 v255, s0, 62
	s_mov_b32 s0, 0
	s_mov_b32 s1, 0xa07f
	v_writelane_b32 v255, s0, 61
	v_writelane_b32 v255, s0, 63
	v_writelane_b32 v255, s1, 59
	s_movk_i32 s0, 0x2c00
	s_cmp_eq_u32 s4, 0
	s_cselect_b32 s0, s0, 0
	s_cmp_eq_u32 s12, 0x100
	s_cselect_b32 s0, s0, 0x7fffffff
	s_mov_b32 s1, 0x9fff
	v_writelane_b32 v255, s0, 57
	v_writelane_b32 v255, s1, 56
	s_branch .Lhdr_common

; #define LAS __attribute__((address_space(3)))
; __device__ __forceinline__ float dot4(f32x4 a, f32x4 b) { return (a.x * b.x + a.y * b.y) + (a.z * b.z + a.w * b.w); }
; __device__ __forceinline__ void attn_unit(const int tid, LAS float* lds, const float* P, const float* qgain, const float* kgain, float* Y, int unit) {
;     const int h = unit & 3, qb = unit >> 2, q0 = qb * 64;
;     LAS float* Qs = lds;
;     LAS float* Ks = Qs + 64 * 132;
;     LAS float* Vs = Ks + 64 * 132;
;     LAS float* Ws = Vs + 64 * 144;
;     LAS float* Tot = Ws + 64 * 68;
;     LAS float* Ar = Tot + 64 * 9;
;     volatile LAS int* flg = (volatile LAS int*)(Ar + 64);
;     const int row = tid >> 3, part = tid & 7;
;     const int lane = tid & 63, wv_ = tid >> 6, r = lane & 15, g = lane >> 4, qs = wv_ >> 1, wodd = wv_ & 1;
;     __syncthreads();
;     {
;         const f32x4* src = (const f32x4*)(P + (size_t)(q0 + row) * DIN + 1 * GW + h * 128 + part * 16);
;         f32x4 v[4]; float ss = 0.f;
; #pragma unroll
;         for (int i = 0; i < 4; ++i) { v[i] = src[i]; ss += dot4(v[i], v[i]); }
;         ss += __shfl_xor(ss, 1); ss += __shfl_xor(ss, 2); ss += __shfl_xor(ss, 4);
;         const float sc = rsqrtf(ss * (1.f / 128.f) + 1e-6f) * 0.08838834764831845f;
; #pragma unroll
;         for (int i = 0; i < 4; ++i) { const f32x4 g4 = ((const f32x4*)(qgain + part * 16))[i]; *(LAS f32x4*)(Qs + row * 132 + part * 16 + i * 4) = v[i] * sc * g4; }
;     }
;     if (tid < 64) Ar[tid] = 0.f;
;     if (tid == 0) *flg = 0;
;     __syncthreads();
;     float qf[32];
; #pragma unroll
;     for (int i4 = 0; i4 < 8; ++i4) { const f32x4 t = *(const LAS f32x4*)(Qs + (qs * 16 + r) * 132 + g * 32 + i4 * 4); qf[i4 * 4] = t.x; qf[i4 * 4 + 1] = t.y; qf[i4 * 4 + 2] = t.z; qf[i4 * 4 + 3] = t.w; }
;     f32x4v oacc[4];
; #pragma unroll
;     for (int s = 0; s < 4; ++s) oacc[s] = (f32x4v){0.f, 0.f, 0.f, 0.f};
;     const int q = tid & 63, kgp = tid >> 6;
;     const int qpos = q0 + q;
;     f32x4 pk_[4], pv_[4];
; __global__ void __launch_bounds__(NTHR, 2) hymba_fwd(Args args) {
;     ...
;             SREP(0) for (int u = bid; u < 4 * (T / 64); u += G) {
;                 int uu = u;
;                 if (G == 256) { const int xcd = bid & 7, idx = bid >> 3, i2 = u / G; uu = (((xcd >> 2) * 64 + 2 * idx + i2) << 2) | (xcd & 3); }
;                 attn_unit(tid, ldsf, P, L.sb_qg, L.sb_kg, WSP(float, WS_Y), uu);
.LBB0_325:
	s_ashr_i32 s1, s0, 31
	v_writelane_b32 v254, s0, 30
	v_ashrrev_i32_e32 v142, 6, v148
	v_and_b32_e32 v168, 15, v148
	v_writelane_b32 v254, s1, 31
	s_lshl_b64 s[0:1], s[0:1], 7
	v_writelane_b32 v255, s0, 7
	s_movk_i32 s28, 0x1000
	v_lshlrev_b32_e32 v143, 4, v148
	v_writelane_b32 v255, s1, 8
	s_add_u32 s0, s18, 0xc200000
	s_addc_u32 s1, s19, 0
	v_writelane_b32 v255, s0, 9
	s_cmpk_lt_i32 s44, 0x200
	s_cselect_b64 s[84:85], -1, 0
	v_writelane_b32 v255, s1, 10
	v_cmp_lt_i32_e64 s[0:1], 1, v142
	v_cmp_gt_i32_e64 s[44:45], 2, v142
	s_and_b64 vcc, exec, s[84:85]
	v_writelane_b32 v255, s0, 11
	v_lshlrev_b32_e32 v116, 2, v168
	s_nop 0
	v_writelane_b32 v255, s1, 12
	s_cbranch_vccz .LBB0_364
	v_readlane_b32 s0, v255, 63
	s_cmp_lg_u32 s0, 0
	s_cbranch_scc1 .Lp5_attn
	v_readlane_b32 s0, v254, 39
	s_bitcmp1_b32 s0, 3
	s_cbranch_scc1 .LBB0_364
.Lp5_attn:
	v_readlane_b32 s0, v255, 7
	v_readlane_b32 s1, v255, 8
	s_lshl_b64 s[0:1], s[0:1], 2
	s_add_u32 s20, s4, s0
	s_addc_u32 s21, s5, s1
	s_add_u32 s0, s6, s0
	s_waitcnt vmcnt(5)
	v_and_b32_e32 v0, 0x70, v143
	s_addc_u32 s1, s7, s1
	v_readlane_b32 s4, v254, 38
	v_ashrrev_i32_e32 v117, 3, v148
	v_lshlrev_b32_e32 v2, 2, v0
	s_movk_i32 s12, 0x210
	s_cmpk_eq_i32 s4, 0x100
	v_readlane_b32 s24, v254, 39
	s_waitcnt vmcnt(4)
	v_mul_lo_u32 v4, v117, s12
	v_add_u32_e32 v5, 0, v2
	v_and_b32_e32 v120, -16, v117
	s_cselect_b64 s[4:5], -1, 0
	s_lshl_b32 s6, s24, 4
	v_mov_b32_e32 v3, v144
	v_add_u32_e32 v118, v5, v4
	v_or_b32_e32 v5, v120, v168
	s_and_b32 s15, s6, 64
	s_lshr_b32 s6, s24, 2
	v_lshrrev_b32_e32 v1, 4, v188
	v_lshl_add_u64 v[80:81], s[20:21], 0, v[2:3]
	v_mul_lo_u32 v6, v5, s12
	v_readlane_b32 s12, v254, 18
	v_readlane_b32 s21, v254, 19
	s_waitcnt vmcnt(2)
	v_mul_u32_u24_e32 v12, 0x110, v188
	v_lshlrev_b32_e32 v13, 5, v142
	s_and_b32 s6, s6, 0x3ffffffe
	v_and_b32_e32 v4, 1, v142
	v_lshlrev_b32_e32 v121, 2, v1
	v_lshl_add_u64 v[82:83], s[0:1], 0, v[2:3]
	s_movk_i32 s0, 0x240
	v_add3_u32 v123, s12, v12, v13
	v_readlane_b32 s1, v254, 20
	v_mov_b32_e32 v12, s21
	s_and_b32 s14, s24, 3
	s_add_i32 s15, s15, s6
	v_lshlrev_b32_e32 v7, 7, v1
	v_add_u32_e32 v9, s21, v2
	v_or_b32_e32 v2, v121, v120
	v_add_u32_e32 v3, s12, v116
	v_mad_u32_u24 v124, v188, 36, s1
	s_movk_i32 s1, 0x110
	v_mad_u32_u24 v1, v1, s0, v12
	v_lshlrev_b32_e32 v12, 8, v4
	s_add_u32 s6, s18, 0x1e200000
	v_add3_u32 v127, v1, v12, v116
	v_lshl_or_b32 v1, v4, 5, v168
	v_lshl_add_u32 v12, v4, 7, v3
	v_mul_lo_u32 v13, v2, s1
	v_lshl_or_b32 v2, v4, 1, 1
	v_lshl_or_b32 v4, v4, 6, v168
	s_addc_u32 s7, s19, 0
	v_lshl_or_b32 v14, v2, 4, v168
	v_lshl_add_u32 v15, v2, 6, v3
	v_lshlrev_b32_e32 v2, 2, v4
	v_mov_b32_e32 v3, v144
	v_lshl_add_u64 v[84:85], s[6:7], 0, v[2:3]
	v_and_b32_e32 v3, 64, v176
	v_xor_b32_e32 v2, 1, v176
	v_add_u32_e32 v3, 64, v3
	v_cmp_lt_i32_e32 vcc, v2, v3
	v_readlane_b32 s20, v254, 17
	v_add_u32_e32 v6, 0, v6
	v_cndmask_b32_e32 v2, v176, v2, vcc
	v_lshlrev_b32_e32 v131, 2, v2
	v_xor_b32_e32 v2, 2, v176
	v_cmp_lt_i32_e32 vcc, v2, v3
	v_add_u32_e32 v8, s12, v121
	v_mul_lo_u32 v10, v117, s0
	v_cndmask_b32_e32 v2, v176, v2, vcc
	v_lshlrev_b32_e32 v132, 2, v2
	v_xor_b32_e32 v2, 4, v176
	v_cmp_lt_i32_e32 vcc, v2, v3
	v_add_u32_e32 v11, 0, v7
	v_mul_lo_u32 v5, v5, s1
	v_mul_u32_u24_e32 v1, 0x210, v1
	v_mul_u32_u24_e32 v14, 0x210, v14
	v_cndmask_b32_e32 v2, v176, v2, vcc
	v_cmp_gt_i32_e64 s[38:39], 64, v148
	v_lshl_add_u32 v119, v148, 2, s20
	v_cmp_eq_u32_e64 s[42:43], 0, v148
	v_lshlrev_b32_e32 v122, 3, v142
	v_lshl_add_u32 v125, v142, 2, v124
	v_lshl_add_u32 v126, v188, 2, s20
	v_cmp_gt_u32_e64 s[46:47], 64, v148
	v_cmp_gt_i32_e64 s[48:49], 0, v142
	v_cmp_gt_i32_e64 s[50:51], 1, v142
	v_cmp_gt_i32_e64 s[52:53], 3, v142
	v_cmp_gt_i32_e64 s[54:55], 4, v142
	v_cmp_gt_i32_e64 s[56:57], 5, v142
	v_cmp_gt_i32_e64 s[58:59], 6, v142
	v_cmp_gt_i32_e64 s[60:61], 7, v142
	v_or_b32_e32 v128, 16, v4
	v_or_b32_e32 v129, 32, v4
	v_or_b32_e32 v130, 48, v4
	v_lshlrev_b32_e32 v133, 2, v2
	v_subrev_u32_e32 v134, 64, v117
	v_lshlrev_b32_e32 v86, 2, v0
	v_add_u32_e32 v135, v6, v7
	v_add_u32_e32 v136, v9, v10
	v_add_u32_e32 v137, v11, v1
	v_add_u32_e32 v138, v12, v13
	v_add_u32_e32 v139, v11, v14
	v_add_u32_e32 v140, v15, v13
	v_add_u32_e32 v141, v8, v5
	s_mov_b32 s20, s24
	s_branch .LBB0_329

; #define LAS __attribute__((address_space(3)))
; #define KEEP16(a, c) asm volatile("" :: "v"(a[0]), "v"(a[1]), "v"(a[2]), "v"(a[3]), "v"(a[4]), "v"(a[5]), "v"(a[6]), "v"(a[7]), "v"(c[0]), "v"(c[1]), "v"(c[2]), "v"(c[3]), "v"(c[4]), "v"(c[5]), "v"(c[6]), "v"(c[7]))
; #define SREP(bit) for (int rep_ = 0; rep_ < (((SUBDUP >> (bit)) & 1) ? 2 : 1); ++rep_)
; __device__ __forceinline__ void rw_pre_unit(const int tid, LAS float* lds, const float* P, const LayerP& L, const float* LT, float* RW, int unit) {
;     constexpr int XS = 532, HS = 276;
;     const int c = tid, t0 = unit * 16;
;     const int lane = tid & 63, wv_ = tid >> 6, r = lane & 15, g = lane >> 4;
;     LAS float* XW = lds; LAS float* XA = XW + 16 * XS; LAS float* XG = XA + 16 * XS; LAS float* HID = XG + 16 * XS;
;     __syncthreads();
;     {
;         const float mu3 = L.rw_mu[3 * GW + c], mu4 = L.rw_mu[4 * GW + c], mu5 = L.rw_mu[5 * GW + c];
;         unsigned mlo = (unsigned)(7 * GW + c); asm volatile("" : "+v"(mlo));
;         const float* P0 = P + (size_t)t0 * DIN;
;         float prev = (t0 > 0) ? (P0 - DIN)[mlo] : 0.f;
;         float mv[16];
; #pragma unroll
;         for (int t = 0; t < 16; ++t) mv[t] = (P0 + (size_t)t * DIN)[mlo];
;         KEEP16(mv, (mv + 8));
; #pragma unroll
;         for (int t = 0; t < 16; ++t) { const float m = mv[t], dm = prev - m; XW[t * XS + c] = m + dm * mu3; XA[t * XS + c] = m + dm * mu4; XG[t * XS + c] = m + dm * mu5; prev = m; }
;     }
;     __syncthreads();
;     {
;         const float* WT; int cb; const LAS float* X;
;         if (wv_ < 2) { WT = LT + LT_WA; cb = wv_ * 32; X = XW; } else if (wv_ < 4) { WT = LT + LT_AA; cb = (wv_ - 2) * 32; X = XA; } else { WT = LT + LT_GA; cb = (wv_ - 4) * 32; X = XG; }
;         f32x4 acc0 = (f32x4){0.f, 0.f, 0.f, 0.f}, acc1 = acc0;
;         unsigned wlo = (unsigned)((cb + r) * GW + 4 * g); asm volatile("" : "+v"(wlo));
;         for (int jc = 0; jc < 4; ++jc) {
;             f32x4 a4[8], b0[8], b1[8];
; #pragma unroll
;             for (int j = 0; j < 8; ++j) { b0[j] = *(const f32x4*)(WT + wlo + 16 * (jc * 8 + j)); b1[j] = *(const f32x4*)(WT + wlo + 16 * GW + 16 * (jc * 8 + j)); }
; __global__ void __launch_bounds__(NTHR, 2) hymba_fwd(Args args) {
;     ...
;             SREP(1) for (int u = bid; u < T / 16; u += G) rw_pre_unit(tid, ldsf, P, L, WSP(float, WS_LORA), WSP(float, WS_RW), u);
.LBB0_364:
	v_readlane_b32 s0, v254, 30
	v_readlane_b32 s1, v254, 31
	s_lshl_b64 s[0:1], s[0:1], 9
	v_writelane_b32 v255, s0, 13
	s_waitcnt vmcnt(5)
	v_cndmask_b32_e64 v0, 0, 1, s[84:85]
	v_ashrrev_i32_e32 v149, 31, v148
	v_writelane_b32 v255, s1, 14
	v_cmp_ne_u32_e64 s[0:1], 1, v0
	v_lshl_add_u32 v145, v148, 2, 0
	s_andn2_b64 vcc, exec, s[84:85]
	v_writelane_b32 v255, s0, 15
	s_barrier
	s_nop 0
	v_writelane_b32 v255, s1, 16
	s_cbranch_vccnz .LBB0_430
	v_readlane_b32 s0, v255, 63
	s_cmp_lg_u32 s0, 1
	s_cbranch_scc1 .Lp5_365_cont
	s_mov_b32 s0, 2
	s_nop 0
	v_writelane_b32 v255, s0, 63
	s_branch .LBB0_430
.Lp5_365_cont:
	v_readlane_b32 s4, v254, 30
	s_mul_i32 s1, s4, 0x3000
	v_readlane_b32 s5, v254, 31
	s_mul_hi_i32 s0, s4, 0x3000
	s_add_u32 s4, s8, s1
	s_addc_u32 s5, s9, s0
	v_readlane_b32 s0, v255, 13
	v_readlane_b32 s1, v255, 14
	s_lshl_b64 s[6:7], s[0:1], 2
	s_add_u32 s0, s10, s6
	s_addc_u32 s1, s11, s7
	s_add_u32 s8, s22, s6
	s_addc_u32 s9, s23, s7
	s_add_u32 s10, s80, s6
	s_addc_u32 s11, s81, s7
	s_add_u32 s14, s82, s6
	s_addc_u32 s15, s83, s7
	s_add_u32 s6, s34, s6
	s_addc_u32 s7, s35, s7
	v_lshl_add_u64 v[0:1], v[148:149], 2, s[4:5]
	s_mov_b64 s[20:21], 0x1800
	s_add_u32 s12, s18, 0x16200000
	v_lshl_add_u64 v[100:101], v[0:1], 0, s[20:21]
	s_mov_b64 s[20:21], 0x2000
	v_writelane_b32 v255, s12, 17
	s_addc_u32 s12, s19, 0
	v_lshl_add_u64 v[102:103], v[0:1], 0, s[20:21]
	s_mov_b64 s[20:21], 0x2800
	v_writelane_b32 v255, s12, 18
	v_lshl_add_u64 v[104:105], v[0:1], 0, s[20:21]
	v_cmp_lt_u32_e64 s[20:21], 3, v142
	v_readlane_b32 s12, v254, 22
	v_lshrrev_b32_e32 v0, 2, v148
	v_writelane_b32 v255, s20, 19
	s_waitcnt vmcnt(4)
	v_mov_b32_e32 v6, s12
	v_lshl_add_u32 v146, v148, 2, s12
	v_writelane_b32 v255, s21, 20
	s_add_u32 s20, s18, 0x29c80000
	s_addc_u32 s21, s19, 0
	v_writelane_b32 v255, s20, 21
	v_and_b32_e32 v154, 12, v0
	v_lshlrev_b32_e32 v0, 7, v142
	v_readlane_b32 s12, v254, 23
	v_writelane_b32 v255, s21, 22
	s_add_u32 s20, s18, 0x29ca0000
	v_add3_u32 v7, s12, v0, v116
	v_mul_u32_u24_e32 v0, 0x450, v168
	s_waitcnt vmcnt(3)
	v_lshlrev_b32_e32 v9, 2, v154
	s_addc_u32 s21, s19, 0
	v_add3_u32 v155, s12, v0, v9
	v_writelane_b32 v255, s20, 23
	v_mov_b32_e32 v1, s19
	v_sub_co_u32_e32 v0, vcc, s18, v9
	v_writelane_b32 v255, s21, 24
	s_nop 0
	v_subbrev_co_u32_e32 v1, vcc, 0, v1, vcc
	s_mov_b64 s[20:21], 0x29cc0000
	v_lshl_add_u64 v[106:107], v[0:1], 0, s[20:21]
	v_lshlrev_b32_e32 v0, 6, v148
	s_movk_i32 s12, 0xf3c0
	v_and_or_b32 v156, v0, s12, v154
	s_movk_i32 s12, 0xc00
	v_or3_b32 v159, v0, v154, s12
	v_and_b32_e32 v0, 0xffffffcf, v148
	v_or_b32_e32 v4, 48, v148
	s_movk_i32 s12, 0x1400
	v_ashrrev_i32_e32 v1, 31, v0
	v_ashrrev_i32_e32 v5, 31, v4
	v_lshlrev_b64 v[2:3], 2, v[0:1]
	v_mad_u32_u24 v163, v154, s12, v4
	v_lshlrev_b64 v[4:5], 2, v[4:5]
	v_or_b32_e32 v1, 16, v0
	v_lshlrev_b32_e32 v10, 9, v154
	v_lshl_add_u64 v[128:129], s[0:1], 0, v[2:3]
	v_lshl_add_u64 v[136:137], s[0:1], 0, v[4:5]
	s_add_i32 s0, 0, 0x8500
	v_mad_u32_u24 v160, v154, s12, v0
	v_mad_u32_u24 v161, v154, s12, v1
	v_add_u32_e32 v164, v10, v0
	v_add_u32_e32 v165, v10, v1
	v_mov_b32_e32 v0, s0
	v_cmp_gt_u32_e32 vcc, 4, v142
	v_mov_b32_e32 v1, 0xffffff80
	v_lshl_add_u64 v[108:109], s[4:5], 0, v[2:3]
	v_lshl_add_u64 v[110:111], s[8:9], 0, v[2:3]
	v_lshl_add_u64 v[112:113], s[10:11], 0, v[2:3]
	v_lshl_add_u64 v[114:115], s[14:15], 0, v[2:3]
	v_lshl_add_u64 v[116:117], s[6:7], 0, v[2:3]
	v_lshl_add_u64 v[118:119], s[4:5], 0, v[4:5]
	v_lshl_add_u64 v[120:121], s[8:9], 0, v[4:5]
	v_lshl_add_u64 v[122:123], s[10:11], 0, v[4:5]
	v_lshl_add_u64 v[124:125], s[14:15], 0, v[4:5]
	v_lshl_add_u64 v[126:127], s[6:7], 0, v[4:5]
	v_cndmask_b32_e32 v0, v6, v0, vcc
	v_cndmask_b32_e32 v1, v1, v251, vcc
	v_mov_b32_e32 v3, 0x29c40000
	v_mov_b32_e32 v4, 0x29c20000
	v_cndmask_b32_e32 v3, v3, v4, vcc
	v_cndmask_b32_e64 v4, v0, 0, s[44:45]
	v_cndmask_b32_e64 v0, v1, 0, s[44:45]
	v_lshl_add_u32 v5, v142, 5, v0
	v_mov_b32_e32 v0, 0x29c00000
	s_mov_b64 s[4:5], 0x1040
	v_cndmask_b32_e64 v0, v3, v0, s[44:45]
	v_mov_b32_e32 v1, v144
	v_mul_u32_u24_e32 v8, 0x450, v154
	v_or_b32_e32 v162, 32, v160
	s_mov_b64 s[8:9], 0x1000
	v_lshl_add_u64 v[132:133], v[108:109], 0, s[4:5]
	s_movk_i32 s6, 0xee00
	s_mov_b64 s[4:5], 0x1080
	v_mul_u32_u24_e32 v2, 0x850, v168
	v_lshl_add_u64 v[140:141], s[18:19], 0, v[0:1]
	v_or_b32_e32 v0, v5, v168
	v_add_u32_e32 v150, 0x63c0, v146
	v_add_u32_e32 v151, 0x6c10, v146
	v_add_u32_e32 v152, 0x7460, v146
	v_add_u32_e32 v153, 0x7cb0, v146
	v_or_b32_e32 v157, 0x400, v156
	v_or_b32_e32 v158, 0x800, v156
	v_lshl_add_u64 v[130:131], v[108:109], 0, s[8:9]
	v_mad_i32_i24 v166, v154, s6, v162
	v_lshl_add_u64 v[134:135], v[108:109], 0, s[4:5]
	v_mad_i32_i24 v167, v154, s6, v163
	v_lshl_add_u64 v[138:139], v[118:119], 0, s[8:9]
	v_lshl_or_b32 v168, v0, 9, v154
	v_add3_u32 v169, v4, v2, v9
	v_add_u32_e32 v170, v7, v8
	v_readlane_b32 s12, v254, 39
	s_branch .LBB0_367

; #define SREP(bit) for (int rep_ = 0; rep_ < (((SUBDUP >> (bit)) & 1) ? 2 : 1); ++rep_)
; __global__ void __launch_bounds__(NTHR, 2) hymba_fwd(Args args) {
;     ...
;             __syncthreads();
;     ...
;             SREP(1) for (int u = bid; u < T / 16; u += G) rw_pre_unit(tid, ldsf, P, L, WSP(float, WS_LORA), WSP(float, WS_RW), u);
;     ...
;             __syncthreads();
.LBB0_430:
	v_readlane_b32 s0, v255, 63
	s_cmp_lg_u32 s0, 0
	s_cbranch_scc1 .Lp5_430_cont
	v_readlane_b32 s0, v254, 39
	s_bitcmp1_b32 s0, 3
	s_cbranch_scc0 .Lp5_430_cont
	s_mov_b32 s0, 1
	s_nop 0
	v_writelane_b32 v255, s0, 63
	v_readlane_b32 s45, v254, 38
	v_readlane_b32 s44, v254, 39
	s_waitcnt vmcnt(0) lgkmcnt(0)
	s_barrier
	s_branch .Lp5_entry
